# speedup vs baseline: 1.0405x; 1.0009x over previous
; __device__ __forceinline__ void partialSM(f32x16& p0, f32x16& p1, float& m_reg, float& mn, float& alpha) {
;     ...
;   float mnC = -mn * C;
;   #pragma unroll
;   for (int r = 0; r < 16; ++r) p0[r] = fmaf(p0[r], C, mnC);
;   #pragma unroll
;   for (int r = 0; r < 16; ++r) p1[r] = fmaf(p1[r], C, mnC);
;   #pragma unroll
;   for (int r = 0; r < 16; ++r) p0[r] = __builtin_amdgcn_exp2f(p0[r]);
; }
; __device__ __forceinline__ void finishSM(f32x16& p0, f32x16& p1, bf16x8& pa0, bf16x8& pa1, bf16x8& pa2, bf16x8& pa3) {
;   #pragma unroll
;   for (int r = 0; r < 16; ++r) p1[r] = __builtin_amdgcn_exp2f(p1[r]);
;     ...
;   PK4(p0, 0, pa0); PK4(p0, 8, pa1); PK4(p1, 0, pa2); PK4(p1, 8, pa3);
;     ...
; }
; __device__ __forceinline__ void qkt(f32x16& p0, f32x16& p1, const char* Ks, const bf16x8* qr, int r32, int hi) {
;   p0 = f32x16{}; p1 = f32x16{};
;   #pragma unroll
;   for (int d0 = 0; d0 < 6; ++d0) { int cb = (d0 * 16 + hi * 8) * 2;
;     bf16x8 b0 = *reinterpret_cast<const bf16x8*>(Ks + r32 * KPITCH + cb);
;     bf16x8 b1 = *reinterpret_cast<const bf16x8*>(Ks + (32 + r32) * KPITCH + cb);
;     p0 = __builtin_amdgcn_mfma_f32_32x32x16_bf16(b0, qr[d0], p0, 0, 0, 0);
;     p1 = __builtin_amdgcn_mfma_f32_32x32x16_bf16(b1, qr[d0], p1, 0, 0, 0); }
; __device__ __forceinline__ void attn_phase(const bf16* __restrict__ qbase, const bf16* __restrict__ Kbase, const bf16* __restrict__ Vbase, bf16* __restrict__ mixbase) {
;     ...
;         if (has_next) {
;           #pragma unroll
;           for (int d0 = 0; d0 < 6; ++d0) qr[d0] = *reinterpret_cast<const bf16x8*>(Qn + d0 * 16);
;         }
.LBB0_523:
	v_cndmask_b32_e64 v148, v132, v181, s[0:1]
	v_mul_f32_e32 v132, 0xbe16c740, v148
	v_pk_fma_f32 v[64:65], v[64:65], s[2:3], v[132:133] op_sel_hi:[1,0,0]
	v_pk_fma_f32 v[66:67], v[66:67], s[2:3], v[132:133] op_sel_hi:[1,0,0]
	v_pk_fma_f32 v[68:69], v[68:69], s[2:3], v[132:133] op_sel_hi:[1,0,0]
	v_pk_fma_f32 v[70:71], v[70:71], s[2:3], v[132:133] op_sel_hi:[1,0,0]
	v_pk_fma_f32 v[72:73], v[72:73], s[2:3], v[132:133] op_sel_hi:[1,0,0]
	v_pk_fma_f32 v[74:75], v[74:75], s[2:3], v[132:133] op_sel_hi:[1,0,0]
	v_pk_fma_f32 v[76:77], v[76:77], s[2:3], v[132:133] op_sel_hi:[1,0,0]
	v_pk_fma_f32 v[78:79], v[78:79], s[2:3], v[132:133] op_sel_hi:[1,0,0]
	v_exp_f32_e32 v150, v64
	v_exp_f32_e32 v153, v65
	v_exp_f32_e32 v154, v66
	v_exp_f32_e32 v157, v67
	v_exp_f32_e32 v158, v68
	v_exp_f32_e32 v181, v69
	v_exp_f32_e32 v221, v70
	v_exp_f32_e32 v222, v71
	v_exp_f32_e32 v136, v72
	v_exp_f32_e32 v147, v73
	v_exp_f32_e32 v149, v74
	v_exp_f32_e32 v151, v75
	v_exp_f32_e32 v152, v76
	v_exp_f32_e32 v155, v77
	v_exp_f32_e32 v156, v78
	v_exp_f32_e32 v159, v79
	v_fmamk_f32 v133, v48, 0x3e16c740, v132
	v_fmamk_f32 v134, v49, 0x3e16c740, v132
	v_fmamk_f32 v135, v50, 0x3e16c740, v132
	v_fmamk_f32 v137, v51, 0x3e16c740, v132
	v_fmamk_f32 v138, v52, 0x3e16c740, v132
	v_fmamk_f32 v139, v53, 0x3e16c740, v132
	v_fmamk_f32 v140, v54, 0x3e16c740, v132
	v_fmamk_f32 v141, v55, 0x3e16c740, v132
	v_fmamk_f32 v142, v56, 0x3e16c740, v132
	v_fmamk_f32 v143, v57, 0x3e16c740, v132
	v_fmamk_f32 v144, v58, 0x3e16c740, v132
	v_fmamk_f32 v145, v59, 0x3e16c740, v132
	v_fmamk_f32 v146, v60, 0x3e16c740, v132
	v_fmamk_f32 v223, v61, 0x3e16c740, v132
	v_fmamk_f32 v224, v62, 0x3e16c740, v132
	v_fmac_f32_e32 v132, 0x3e16c740, v63
	s_waitcnt lgkmcnt(0)
	s_barrier
	ds_read_b128 v[48:51], v219 offset:16384
	ds_read_b128 v[226:229], v219 offset:16416
	ds_read_b128 v[64:67], v219 offset:23040
	ds_read_b128 v[230:233], v219 offset:23072
	s_andn2_b64 vcc, exec, s[46:47]
	s_waitcnt lgkmcnt(3)
	v_mfma_f32_32x32x16_bf16 v[48:63], v[48:51], v[80:83], 0
	s_waitcnt lgkmcnt(1)
	v_mfma_f32_32x32x16_bf16 v[64:79], v[64:67], v[80:83], 0
	v_mfma_f32_32x32x16_bf16 v[48:63], v[226:229], v[84:87], v[48:63]
	s_waitcnt lgkmcnt(0)
	v_mfma_f32_32x32x16_bf16 v[64:79], v[230:233], v[84:87], v[64:79]
	ds_read_b128 v[226:229], v219 offset:16448
	ds_read_b128 v[230:233], v219 offset:16480
	s_waitcnt lgkmcnt(1)
	v_mfma_f32_32x32x16_bf16 v[48:63], v[226:229], v[88:91], v[48:63]
	ds_read_b128 v[226:229], v219 offset:23104
	ds_read_b128 v[234:237], v219 offset:23136
	s_waitcnt lgkmcnt(1)
	v_mfma_f32_32x32x16_bf16 v[64:79], v[226:229], v[88:91], v[64:79]
	v_mfma_f32_32x32x16_bf16 v[48:63], v[230:233], v[92:95], v[48:63]
	ds_read_b128 v[226:229], v219 offset:16512
	ds_read_b128 v[230:233], v219 offset:16544
	s_waitcnt lgkmcnt(2)
	v_mfma_f32_32x32x16_bf16 v[64:79], v[234:237], v[92:95], v[64:79]
	s_waitcnt lgkmcnt(1)
	v_mfma_f32_32x32x16_bf16 v[48:63], v[226:229], v[96:99], v[48:63]
	ds_read_b128 v[226:229], v219 offset:23168
	ds_read_b128 v[234:237], v219 offset:23200
	s_waitcnt lgkmcnt(1)
	v_mfma_f32_32x32x16_bf16 v[64:79], v[226:229], v[96:99], v[64:79]
	v_mfma_f32_32x32x16_bf16 v[48:63], v[230:233], v[100:103], v[48:63]
	s_waitcnt lgkmcnt(0)
	v_mfma_f32_32x32x16_bf16 v[64:79], v[234:237], v[100:103], v[64:79]
	s_cbranch_vccnz .LBB0_527
	s_and_b64 vcc, exec, s[6:7]
	s_cbranch_vccnz .LBB0_526
	global_load_dwordx4 v[80:83], v[188:189], off
	global_load_dwordx4 v[84:87], v[188:189], off offset:32
	global_load_dwordx4 v[88:91], v[188:189], off offset:64
	global_load_dwordx4 v[92:95], v[188:189], off offset:96
	global_load_dwordx4 v[96:99], v[188:189], off offset:128
	global_load_dwordx4 v[100:103], v[188:189], off offset:160

; __device__ __forceinline__ void partialSM(f32x16& p0, f32x16& p1, float& m_reg, float& mn, float& alpha) {
;     ...
;   float mnC = -mn * C;
;   #pragma unroll
;   for (int r = 0; r < 16; ++r) p0[r] = fmaf(p0[r], C, mnC);
;   #pragma unroll
;   for (int r = 0; r < 16; ++r) p1[r] = fmaf(p1[r], C, mnC);
.LBB0_539:
	v_cndmask_b32_e64 v181, v132, v148, s[0:1]
	v_mul_f32_e32 v132, 0xbe16c740, v181
	v_mov_b32_e32 v133, v132
	v_pk_fma_f32 v[48:49], v[48:49], s[2:3], v[132:133] op_sel_hi:[1,0,0]
	v_pk_fma_f32 v[50:51], v[50:51], s[2:3], v[132:133] op_sel_hi:[1,0,0]
	v_pk_fma_f32 v[52:53], v[52:53], s[2:3], v[132:133] op_sel_hi:[1,0,0]
	v_pk_fma_f32 v[54:55], v[54:55], s[2:3], v[132:133] op_sel_hi:[1,0,0]
	v_pk_fma_f32 v[56:57], v[56:57], s[2:3], v[132:133] op_sel_hi:[1,0,0]
	v_pk_fma_f32 v[58:59], v[58:59], s[2:3], v[132:133] op_sel_hi:[1,0,0]
	v_pk_fma_f32 v[60:61], v[60:61], s[2:3], v[132:133] op_sel_hi:[1,0,0]
	v_fmamk_f32 v62, v62, 0x3e16c740, v132
	v_fmac_f32_e32 v133, 0x3e16c740, v63
	v_exp_f32_e32 v226, v48
	v_exp_f32_e32 v230, v49
	v_exp_f32_e32 v227, v50
	v_exp_f32_e32 v231, v51
	v_exp_f32_e32 v228, v52
	v_exp_f32_e32 v232, v53
	v_exp_f32_e32 v225, v54
	v_exp_f32_e32 v229, v55
	v_exp_f32_e32 v206, v56
	v_exp_f32_e32 v223, v57
	v_exp_f32_e32 v207, v58
	v_exp_f32_e32 v224, v59
	v_exp_f32_e32 v205, v60
	v_exp_f32_e32 v222, v61
	v_exp_f32_e32 v204, v62
	v_exp_f32_e32 v221, v133
	s_add_i32 s41, s41, 2
	s_add_u32 s42, s42, 0x6000
	v_pk_fma_f32 v[152:153], v[64:65], s[2:3], v[132:133] op_sel_hi:[1,0,0]
	v_pk_fma_f32 v[150:151], v[66:67], s[2:3], v[132:133] op_sel_hi:[1,0,0]
	v_pk_fma_f32 v[148:149], v[68:69], s[2:3], v[132:133] op_sel_hi:[1,0,0]
	v_pk_fma_f32 v[146:147], v[70:71], s[2:3], v[132:133] op_sel_hi:[1,0,0]
	v_pk_fma_f32 v[144:145], v[72:73], s[2:3], v[132:133] op_sel_hi:[1,0,0]
	v_pk_fma_f32 v[158:159], v[74:75], s[2:3], v[132:133] op_sel_hi:[1,0,0]
	v_pk_fma_f32 v[156:157], v[76:77], s[2:3], v[132:133] op_sel_hi:[1,0,0]
	v_pk_fma_f32 v[154:155], v[78:79], s[2:3], v[132:133] op_sel_hi:[1,0,0]
	v_lshl_add_u64 v[198:199], v[198:199], 0, s[14:15]
	s_addc_u32 s43, s43, 0
	s_and_b64 vcc, exec, s[46:47]
	s_waitcnt lgkmcnt(0)
	s_barrier
	s_cbranch_vccnz .LBB0_509
	s_branch .LBB0_513
